# v8 + seam grid barrier: every workgroup polls the top counter directly (target = gen*nXCD), removing the TOPGEN and per-XCD XGEN release hops
# speedup vs baseline: 1.0012x; 1.0012x over previous
; #define LAS __attribute__((address_space(3)))
; __device__ __forceinline__ unsigned xb_ld(unsigned* p)              { return __hip_atomic_load(p, __ATOMIC_RELAXED, __HIP_MEMORY_SCOPE_AGENT); }
; __device__ __forceinline__ unsigned xb_add(unsigned* p, unsigned v) { return __hip_atomic_fetch_add(p, v, __ATOMIC_RELAXED, __HIP_MEMORY_SCOPE_AGENT); }
; __device__ __forceinline__ unsigned xb_xcc_id() { return (unsigned)__builtin_amdgcn_s_getreg((3 << 11) | 20) & 0xFu; }
; #define XB_SPIN(cond, bar) do { unsigned _sp = 0; while (cond) { __builtin_amdgcn_s_sleep(1); \
;     if ((++_sp & 255u) == 0u) { if (xb_ld(&(bar)[XB_TMO])) break; if (_sp > XB_SPIN_CAP) { atomicAdd(&(bar)[XB_TMO], 1u); break; } } } } while (0)
; __device__ __forceinline__ void xcd_barrier(unsigned* bar, volatile LAS unsigned* st, const int tid) {
;     asm volatile("s_waitcnt vmcnt(0)" ::: "memory");
;     __syncthreads();
;     if (tid == 0) {
;         const unsigned x = xb_xcc_id();
;         __builtin_amdgcn_s_waitcnt(0);
;         unsigned nloc = st[0], nx = st[1];
;         if (nloc == 0u) { xcd_barrier_complete(bar, x, nloc, nx); st[0] = nloc; st[1] = nx; }
;         const unsigned old = xb_add(&bar[XB_XSUB(x)], 1u);
;         const unsigned gen = old / nloc;
;         if (old + 1u == (gen + 1u) * nloc) {
;             __builtin_amdgcn_fence(__ATOMIC_RELEASE, "agent");
;             asm volatile("s_waitcnt vmcnt(0)" ::: "memory");
;             const unsigned og = xb_add(&bar[XB_TOP], 1u);
;             const unsigned tg = og / nx;
;             if (og + 1u == (tg + 1u) * nx) xb_add(&bar[XB_TOPGEN], 1u);
;             else XB_SPIN(xb_ld(&bar[XB_TOPGEN]) == tg, bar);
;             __builtin_amdgcn_fence(__ATOMIC_ACQUIRE, "agent");
;             xb_add(&bar[XB_XGEN(x)], 1u);
;             asm volatile("s_waitcnt vmcnt(0)" ::: "memory");
;         } else {
;             XB_SPIN(xb_ld(&bar[XB_XGEN(x)]) == gen, bar);
;             __builtin_amdgcn_fence(__ATOMIC_ACQUIRE, "agent");
;             asm volatile("s_waitcnt vmcnt(0)" ::: "memory");
;         }
;     }
;     __syncthreads();
; }
.LBB0_765:
	s_add_i32 s67, s67, 1
	v_readlane_b32 s84, v255, 31
	s_cmp_ge_i32 s67, s61
	s_mov_b64 s[0:1], -1
	v_readlane_b32 s86, v255, 33
	v_readlane_b32 s87, v255, 34
	v_readlane_b32 s26, v255, 46
	v_readlane_b32 s85, v255, 32
	v_readlane_b32 s27, v255, 47
	s_cbranch_scc1 .LBB0_118
	s_waitcnt vmcnt(0)
	v_cmp_eq_u32_e32 vcc, 0, v236
	s_waitcnt vmcnt(0) lgkmcnt(0)
	s_barrier
	s_and_saveexec_b64 s[30:31], vcc
	s_cbranch_execz .LBB0_117
	v_readlane_b32 s1, v255, 9
	s_getreg_b32 s0, hwreg(HW_REG_XCC_ID, 0, 4)
	v_mov_b32_e32 v0, s1
	ds_read_b32 v2, v0
	v_readlane_b32 s1, v255, 10
	s_and_b32 s58, s0, 15
	v_mov_b32_e32 v0, s1
	ds_read_b32 v0, v0
	s_lshl_b32 s0, s58, 8
	s_add_u32 s0, s82, s0
	s_addc_u32 s1, s83, 0
	s_add_u32 s0, s0, 0x9400
	s_addc_u32 s1, s1, 0
	s_add_u32 s6, s82, 0xb400
	s_addc_u32 s7, s83, 0
	v_mov_b32_e32 v4, 0
	v_mov_b32_e32 v1, 1
	global_atomic_add v3, v4, v1, s[0:1] sc0
	s_waitcnt lgkmcnt(0)
	s_nop 0
	v_readfirstlane_b32 s2, v2
	v_readfirstlane_b32 s3, v0
	s_nop 3
	s_mul_i32 s4, s67, s2
	s_mul_i32 s5, s67, s3
	s_mov_b32 s8, 0
	s_waitcnt vmcnt(0)
	v_add_u32_e32 v3, 1, v3
	v_cmp_eq_u32_e32 vcc, s4, v3
	s_cbranch_vccz .Lxb_poll
	buffer_wbl2 sc1
	s_waitcnt vmcnt(0)
	global_atomic_add v4, v1, s[6:7]
.Lxb_poll:
	global_load_dword v3, v4, s[6:7] sc1
	s_add_i32 s8, s8, 1
	s_waitcnt vmcnt(0)
	v_cmp_le_u32_e32 vcc, s5, v3
	s_cbranch_vccnz .Lxb_done
	s_cmp_gt_u32 s8, 0x40000
	s_cbranch_scc1 .Lxb_done
	s_sleep 1
	s_branch .Lxb_poll
.Lxb_done:
	s_waitcnt vmcnt(0) lgkmcnt(0)
	buffer_inv sc1
	s_waitcnt vmcnt(0)
	s_branch .LBB0_117
